# P1 rope epilogue: second half-tile's cos/sin loads issued inside the first half's processing (into registers the first half is done with), waits re-counted
# speedup vs baseline: 1.0049x; 1.0049x over previous
; __device__ __forceinline__ unsigned pk_bf16(float lo, float hi) { typedef __bf16 b2 __attribute__((ext_vector_type(2))); f32x2 v = {lo, hi}; b2 b = __builtin_convertvector(v, b2); return __builtin_bit_cast(unsigned, b); }
;     __device__ __forceinline__ void operator()(const f32x4 (&acc)[2][2][4][2], const Unit& u, int wr, int wc, int fr, int fq) const {
;     ...
;             if (pn < 12) {
;                 const float sc = (pn < 6) ? 0.125f * 1.4426950408889634f : 1.0f;
;                 const float* cosT = (const float*)(ws + WS_COS); const float* sinT = (const float*)(ws + WS_SIN);
;                 const int jb = 16 * (wc & 1) + 4 * fq;
; #pragma unroll
;                 for (int ai = 0; ai < 2; ++ai) { f32x4 cc[4], ss[4];
; #pragma unroll
;                     for (int m = 0; m < 4; ++m) { const int row = row0 + ai * 128 + m * 16; cc[m] = *(const f32x4*)(cosT + (size_t)row * 32 + jb); ss[m] = *(const f32x4*)(sinT + (size_t)row * 32 + jb); }
; #pragma unroll
;                     for (int m = 0; m < 4; ++m) { const int row = row0 + ai * 128 + m * 16; const f32x4 c = cc[m], s = ss[m];
;                         u16* rowp = ZB + ((size_t)(pn * 4 + (wc >> 1)) * TT + row) * 64 + (lc & 63);
; #pragma unroll
;                         for (int bj = 0; bj < 2; ++bj) { const f32x4 v0 = acc[ai][bj][m][0], v1 = acc[ai][bj][m][1]; u32x4 w;
;                             w.x = pk_bf16((v0[0] * c[0] - v0[1] * s[0]) * sc, (v0[1] * c[0] + v0[0] * s[0]) * sc);
;                             w.y = pk_bf16((v0[2] * c[1] - v0[3] * s[1]) * sc, (v0[3] * c[1] + v0[2] * s[1]) * sc);
;                             w.z = pk_bf16((v1[0] * c[2] - v1[1] * s[2]) * sc, (v1[1] * c[2] + v1[0] * s[2]) * sc);
;                             w.w = pk_bf16((v1[2] * c[3] - v1[3] * s[3]) * sc, (v1[3] * c[3] + v1[2] * s[3]) * sc);
;                             *(u32x4*)(rowp + (size_t)bj * 2 * TT * 64) = w; } } }
.LBB0_137:
	v_lshlrev_b64 v[170:171], 7, v[128:129]
	v_lshl_add_u64 v[130:131], v[158:159], 0, v[170:171]
	global_load_dwordx4 v[182:185], v[130:131], off
	v_lshl_add_u64 v[130:131], v[156:157], 0, v[170:171]
	global_load_dwordx4 v[190:193], v[130:131], off
	v_or_b32_e32 v130, 16, v128
	v_ashrrev_i32_e32 v131, 31, v130
	v_lshlrev_b64 v[186:187], 7, v[130:131]
	v_lshl_add_u64 v[130:131], v[156:157], 0, v[186:187]
	v_lshl_add_u64 v[132:133], v[158:159], 0, v[186:187]
	global_load_dwordx4 v[194:197], v[130:131], off
	global_load_dwordx4 v[198:201], v[132:133], off
	v_or_b32_e32 v130, 32, v128
	v_or_b32_e32 v128, 48, v128
	v_ashrrev_i32_e32 v131, 31, v130
	v_ashrrev_i32_e32 v129, 31, v128
	v_lshlrev_b64 v[202:203], 7, v[130:131]
	v_lshlrev_b64 v[172:173], 7, v[128:129]
	v_lshl_add_u64 v[128:129], v[156:157], 0, v[202:203]
	v_lshl_add_u64 v[130:131], v[158:159], 0, v[202:203]
	v_lshl_add_u64 v[132:133], v[156:157], 0, v[172:173]
	v_lshl_add_u64 v[134:135], v[158:159], 0, v[172:173]
	global_load_dwordx4 v[136:139], v[128:129], off
	global_load_dwordx4 v[140:143], v[130:131], off
	s_nop 0
	global_load_dwordx4 v[128:131], v[132:133], off
	s_nop 0
	global_load_dwordx4 v[132:135], v[134:135], off
	s_cmp_lt_i32 s94, 6
	s_cselect_b64 vcc, -1, 0
	s_lshl_b32 s6, s94, 2
	s_or_b32 s40, s6, s70
	s_ashr_i32 s41, s40, 31
	v_cndmask_b32_e32 v152, 1.0, v180, vcc
	s_lshl_b64 s[40:41], s[40:41], 21
	v_lshl_add_u64 v[168:169], v[154:155], 0, s[40:41]
	v_lshl_add_u64 v[204:205], v[168:169], 0, v[170:171]
	s_waitcnt vmcnt(0)
	v_pk_mul_f32 v[206:207], v[124:125], v[182:183] op_sel_hi:[1,0]
	v_pk_mul_f32 v[208:209], v[126:127], v[182:183] op_sel:[0,1]
	v_pk_mul_f32 v[210:211], v[120:121], v[184:185] op_sel_hi:[1,0]
	v_mov_b32_e32 v214, v185
	v_mov_b32_e32 v212, v193
	v_pk_fma_f32 v[218:219], v[124:125], v[190:191], v[206:207] op_sel:[0,0,1] op_sel_hi:[1,1,0] neg_lo:[0,0,1] neg_hi:[0,0,1]
	v_pk_fma_f32 v[124:125], v[124:125], v[190:191], v[206:207] op_sel:[0,0,1] op_sel_hi:[1,0,0]
	v_pk_fma_f32 v[206:207], v[126:127], v[190:191], v[208:209] op_sel:[0,1,1] op_sel_hi:[1,1,0] neg_lo:[0,0,1] neg_hi:[0,0,1]
	v_pk_fma_f32 v[126:127], v[126:127], v[190:191], v[208:209] op_sel:[0,1,1] op_sel_hi:[1,1,0]
	v_pk_fma_f32 v[208:209], v[120:121], v[192:193], v[210:211] op_sel:[0,0,1] op_sel_hi:[1,1,0] neg_lo:[0,0,1] neg_hi:[0,0,1]
	v_pk_fma_f32 v[120:121], v[120:121], v[192:193], v[210:211] op_sel:[0,0,1] op_sel_hi:[1,0,0]
	v_pk_mul_f32 v[210:211], v[122:123], v[214:215] op_sel_hi:[1,0]
	v_pk_mul_f32 v[216:217], v[116:117], v[182:183] op_sel_hi:[1,0]
	v_pk_mul_f32 v[182:183], v[118:119], v[182:183] op_sel:[0,1]
	v_pk_mul_f32 v[184:185], v[112:113], v[184:185] op_sel_hi:[1,0]
	v_mov_b32_e32 v209, v121
	v_pk_fma_f32 v[120:121], v[122:123], v[212:213], v[210:211] op_sel:[0,0,1] op_sel_hi:[1,0,0] neg_lo:[0,0,1] neg_hi:[0,0,1]
	v_pk_fma_f32 v[122:123], v[122:123], v[212:213], v[210:211] op_sel:[0,0,1] op_sel_hi:[1,0,0]
	v_pk_fma_f32 v[220:221], v[116:117], v[190:191], v[216:217] op_sel:[0,0,1] op_sel_hi:[1,1,0] neg_lo:[0,0,1] neg_hi:[0,0,1]
	v_pk_fma_f32 v[116:117], v[116:117], v[190:191], v[216:217] op_sel:[0,0,1] op_sel_hi:[1,0,0]
	v_pk_fma_f32 v[216:217], v[118:119], v[190:191], v[182:183] op_sel:[0,1,1] op_sel_hi:[1,1,0] neg_lo:[0,0,1] neg_hi:[0,0,1]
	v_pk_fma_f32 v[118:119], v[118:119], v[190:191], v[182:183] op_sel:[0,1,1] op_sel_hi:[1,1,0]
	v_pk_fma_f32 v[182:183], v[112:113], v[192:193], v[184:185] op_sel:[0,0,1] op_sel_hi:[1,1,0] neg_lo:[0,0,1] neg_hi:[0,0,1]
	v_pk_fma_f32 v[112:113], v[112:113], v[192:193], v[184:185] op_sel:[0,0,1] op_sel_hi:[1,0,0]
	v_pk_mul_f32 v[184:185], v[114:115], v[214:215] op_sel_hi:[1,0]
	v_mov_b32_e32 v219, v125
	v_mov_b32_e32 v207, v127
	v_mov_b32_e32 v121, v123
	v_mov_b32_e32 v221, v117
	v_mov_b32_e32 v217, v119
	v_mov_b32_e32 v183, v113
	v_pk_fma_f32 v[124:125], v[114:115], v[212:213], v[184:185] op_sel:[0,0,1] op_sel_hi:[1,0,0] neg_lo:[0,0,1] neg_hi:[0,0,1]
	v_pk_fma_f32 v[112:113], v[114:115], v[212:213], v[184:185] op_sel:[0,0,1] op_sel_hi:[1,0,0]
	v_pk_mul_f32 v[114:115], v[152:153], v[218:219] op_sel_hi:[0,1]
	v_pk_mul_f32 v[116:117], v[152:153], v[206:207] op_sel_hi:[0,1]
	v_pk_mul_f32 v[118:119], v[152:153], v[208:209] op_sel_hi:[0,1]
	v_pk_mul_f32 v[120:121], v[152:153], v[120:121] op_sel_hi:[0,1]
	v_pk_mul_f32 v[122:123], v[152:153], v[220:221] op_sel_hi:[0,1]
	v_mov_b32_e32 v125, v113
	v_cvt_pk_bf16_f32 v112, v114, v115
	v_cvt_pk_bf16_f32 v113, v116, v117
	v_cvt_pk_bf16_f32 v114, v118, v119
	v_cvt_pk_bf16_f32 v115, v120, v121
	v_pk_mul_f32 v[126:127], v[152:153], v[216:217] op_sel_hi:[0,1]
	v_pk_mul_f32 v[182:183], v[152:153], v[182:183] op_sel_hi:[0,1]
	v_cvt_pk_bf16_f32 v116, v122, v123
	v_pk_mul_f32 v[122:123], v[152:153], v[124:125] op_sel_hi:[0,1]
	global_store_dwordx4 v[204:205], v[112:115], off
	v_cvt_pk_bf16_f32 v117, v126, v127
	v_cvt_pk_bf16_f32 v118, v182, v183
	v_add_co_u32_e32 v112, vcc, s89, v204
	v_cvt_pk_bf16_f32 v119, v122, v123
	s_nop 0
	v_addc_co_u32_e32 v113, vcc, 0, v205, vcc
	v_pk_mul_f32 v[114:115], v[108:109], v[198:199] op_sel_hi:[1,0]
	global_store_dwordx4 v[112:113], v[116:119], off
	v_lshl_add_u64 v[246:247], v[170:171], 0, s[22:23]
	v_lshl_add_u64 v[250:251], v[158:159], 0, v[246:247]
	global_load_dwordx4 v[236:239], v[250:251], off
	v_lshl_add_u64 v[246:247], v[170:171], 0, s[22:23]
	v_lshl_add_u64 v[250:251], v[156:157], 0, v[246:247]
	global_load_dwordx4 v[242:245], v[250:251], off
	v_lshl_add_u64 v[246:247], v[170:171], 0, s[24:25]
	v_lshl_add_u64 v[250:251], v[158:159], 0, v[246:247]
	global_load_dwordx4 v[182:185], v[250:251], off
	v_lshl_add_u64 v[246:247], v[170:171], 0, s[24:25]
; __device__ __forceinline__ unsigned pk_bf16(float lo, float hi) { typedef __bf16 b2 __attribute__((ext_vector_type(2))); f32x2 v = {lo, hi}; b2 b = __builtin_convertvector(v, b2); return __builtin_bit_cast(unsigned, b); }
;     __device__ __forceinline__ void operator()(const f32x4 (&acc)[2][2][4][2], const Unit& u, int wr, int wc, int fr, int fq) const {
;     ...
;                 for (int ai = 0; ai < 2; ++ai) { f32x4 cc[4], ss[4];
; #pragma unroll
;                     for (int m = 0; m < 4; ++m) { const int row = row0 + ai * 128 + m * 16; cc[m] = *(const f32x4*)(cosT + (size_t)row * 32 + jb); ss[m] = *(const f32x4*)(sinT + (size_t)row * 32 + jb); }
; #pragma unroll
;                     for (int m = 0; m < 4; ++m) { const int row = row0 + ai * 128 + m * 16; const f32x4 c = cc[m], s = ss[m];
;                         u16* rowp = ZB + ((size_t)(pn * 4 + (wc >> 1)) * TT + row) * 64 + (lc & 63);
; #pragma unroll
;                         for (int bj = 0; bj < 2; ++bj) { const f32x4 v0 = acc[ai][bj][m][0], v1 = acc[ai][bj][m][1]; u32x4 w;
;                             w.x = pk_bf16((v0[0] * c[0] - v0[1] * s[0]) * sc, (v0[1] * c[0] + v0[0] * s[0]) * sc);
;                             w.y = pk_bf16((v0[2] * c[1] - v0[3] * s[1]) * sc, (v0[3] * c[1] + v0[2] * s[1]) * sc);
;                             w.z = pk_bf16((v1[0] * c[2] - v1[1] * s[2]) * sc, (v1[1] * c[2] + v1[0] * s[2]) * sc);
;                             w.w = pk_bf16((v1[2] * c[3] - v1[3] * s[3]) * sc, (v1[3] * c[3] + v1[2] * s[3]) * sc);
;                             *(u32x4*)(rowp + (size_t)bj * 2 * TT * 64) = w; } } }
	v_lshl_add_u64 v[250:251], v[156:157], 0, v[246:247]
	global_load_dwordx4 v[190:193], v[250:251], off
	v_lshl_add_u64 v[112:113], v[168:169], 0, v[186:187]
	s_nop 0
	v_pk_fma_f32 v[116:117], v[108:109], v[194:195], v[114:115] op_sel:[0,0,1] op_sel_hi:[1,1,0] neg_lo:[0,0,1] neg_hi:[0,0,1]
	v_pk_fma_f32 v[108:109], v[108:109], v[194:195], v[114:115] op_sel:[0,0,1] op_sel_hi:[1,0,0]
	v_pk_mul_f32 v[114:115], v[110:111], v[198:199] op_sel:[0,1]
	v_mov_b32_e32 v117, v109
	v_pk_mul_f32 v[108:109], v[152:153], v[116:117] op_sel_hi:[0,1]
	v_pk_fma_f32 v[116:117], v[110:111], v[194:195], v[114:115] op_sel:[0,1,1] op_sel_hi:[1,1,0] neg_lo:[0,0,1] neg_hi:[0,0,1]
	v_pk_fma_f32 v[110:111], v[110:111], v[194:195], v[114:115] op_sel:[0,1,1] op_sel_hi:[1,1,0]
	v_cvt_pk_bf16_f32 v108, v108, v109
	v_mov_b32_e32 v117, v111
	v_pk_mul_f32 v[110:111], v[152:153], v[116:117] op_sel_hi:[0,1]
	v_cvt_pk_bf16_f32 v109, v110, v111
	v_pk_mul_f32 v[110:111], v[104:105], v[200:201] op_sel_hi:[1,0]
	s_nop 0
	v_pk_fma_f32 v[114:115], v[104:105], v[196:197], v[110:111] op_sel:[0,0,1] op_sel_hi:[1,1,0] neg_lo:[0,0,1] neg_hi:[0,0,1]
	v_pk_fma_f32 v[104:105], v[104:105], v[196:197], v[110:111] op_sel:[0,0,1] op_sel_hi:[1,0,0]
	s_nop 0
	v_mov_b32_e32 v115, v105
	v_pk_mul_f32 v[104:105], v[152:153], v[114:115] op_sel_hi:[0,1]
	v_mov_b32_e32 v114, v201
	v_cvt_pk_bf16_f32 v110, v104, v105
	v_mov_b32_e32 v104, v197
	v_pk_mul_f32 v[116:117], v[106:107], v[114:115] op_sel_hi:[1,0]
	s_nop 0
	v_pk_fma_f32 v[118:119], v[106:107], v[104:105], v[116:117] op_sel:[0,0,1] op_sel_hi:[1,0,0] neg_lo:[0,0,1] neg_hi:[0,0,1]
	v_pk_fma_f32 v[106:107], v[106:107], v[104:105], v[116:117] op_sel:[0,0,1] op_sel_hi:[1,0,0]
	s_nop 0
	v_mov_b32_e32 v119, v107
	v_pk_mul_f32 v[106:107], v[152:153], v[118:119] op_sel_hi:[0,1]
	v_cvt_pk_bf16_f32 v111, v106, v107
	v_pk_mul_f32 v[106:107], v[100:101], v[198:199] op_sel_hi:[1,0]
	global_store_dwordx4 v[112:113], v[108:111], off
	s_nop 1
	v_pk_fma_f32 v[108:109], v[100:101], v[194:195], v[106:107] op_sel:[0,0,1] op_sel_hi:[1,1,0] neg_lo:[0,0,1] neg_hi:[0,0,1]
	v_pk_fma_f32 v[100:101], v[100:101], v[194:195], v[106:107] op_sel:[0,0,1] op_sel_hi:[1,0,0]
	v_pk_mul_f32 v[106:107], v[102:103], v[198:199] op_sel:[0,1]
	v_mov_b32_e32 v109, v101
	v_pk_mul_f32 v[100:101], v[152:153], v[108:109] op_sel_hi:[0,1]
	v_pk_fma_f32 v[108:109], v[102:103], v[194:195], v[106:107] op_sel:[0,1,1] op_sel_hi:[1,1,0] neg_lo:[0,0,1] neg_hi:[0,0,1]
	v_pk_fma_f32 v[102:103], v[102:103], v[194:195], v[106:107] op_sel:[0,1,1] op_sel_hi:[1,1,0]
	v_cvt_pk_bf16_f32 v100, v100, v101
	v_mov_b32_e32 v109, v103
	v_pk_mul_f32 v[102:103], v[152:153], v[108:109] op_sel_hi:[0,1]
	v_cvt_pk_bf16_f32 v101, v102, v103
	v_pk_mul_f32 v[102:103], v[92:93], v[200:201] op_sel_hi:[1,0]
	s_nop 0
	v_pk_fma_f32 v[106:107], v[92:93], v[196:197], v[102:103] op_sel:[0,0,1] op_sel_hi:[1,1,0] neg_lo:[0,0,1] neg_hi:[0,0,1]
	v_pk_fma_f32 v[92:93], v[92:93], v[196:197], v[102:103] op_sel:[0,0,1] op_sel_hi:[1,0,0]
	s_nop 0
	v_mov_b32_e32 v107, v93
	v_pk_mul_f32 v[92:93], v[152:153], v[106:107] op_sel_hi:[0,1]
	v_cvt_pk_bf16_f32 v102, v92, v93
	v_pk_mul_f32 v[92:93], v[94:95], v[114:115] op_sel_hi:[1,0]
	s_nop 0
	v_pk_fma_f32 v[106:107], v[94:95], v[104:105], v[92:93] op_sel:[0,0,1] op_sel_hi:[1,0,0] neg_lo:[0,0,1] neg_hi:[0,0,1]
	v_pk_fma_f32 v[92:93], v[94:95], v[104:105], v[92:93] op_sel:[0,0,1] op_sel_hi:[1,0,0]
	s_nop 0
	v_mov_b32_e32 v107, v93
	v_pk_mul_f32 v[92:93], v[152:153], v[106:107] op_sel_hi:[0,1]
	v_cvt_pk_bf16_f32 v103, v92, v93
	v_add_co_u32_e32 v92, vcc, s89, v112
	s_nop 1
	v_addc_co_u32_e32 v93, vcc, 0, v113, vcc
	global_store_dwordx4 v[92:93], v[100:103], off
	v_lshl_add_u64 v[246:247], v[170:171], 0, s[26:27]
	v_lshl_add_u64 v[250:251], v[156:157], 0, v[246:247]
	global_load_dwordx4 v[194:197], v[250:251], off
	v_lshl_add_u64 v[246:247], v[170:171], 0, s[26:27]
	v_lshl_add_u64 v[250:251], v[158:159], 0, v[246:247]
	global_load_dwordx4 v[198:201], v[250:251], off
	v_pk_mul_f32 v[92:93], v[96:97], v[140:141] op_sel_hi:[1,0]
	s_nop 0
	v_pk_fma_f32 v[94:95], v[96:97], v[136:137], v[92:93] op_sel:[0,0,1] op_sel_hi:[1,1,0] neg_lo:[0,0,1] neg_hi:[0,0,1]
	v_pk_fma_f32 v[92:93], v[96:97], v[136:137], v[92:93] op_sel:[0,0,1] op_sel_hi:[1,0,0]
	v_lshl_add_u64 v[100:101], v[168:169], 0, v[202:203]
	v_mov_b32_e32 v95, v93
	v_pk_mul_f32 v[92:93], v[152:153], v[94:95] op_sel_hi:[0,1]
	v_pk_mul_f32 v[94:95], v[98:99], v[140:141] op_sel:[0,1]
	v_cvt_pk_bf16_f32 v92, v92, v93
	v_pk_fma_f32 v[96:97], v[98:99], v[136:137], v[94:95] op_sel:[0,1,1] op_sel_hi:[1,1,0] neg_lo:[0,0,1] neg_hi:[0,0,1]
	v_pk_fma_f32 v[94:95], v[98:99], v[136:137], v[94:95] op_sel:[0,1,1] op_sel_hi:[1,1,0]
	s_nop 0
	v_mov_b32_e32 v97, v95
	v_pk_mul_f32 v[94:95], v[152:153], v[96:97] op_sel_hi:[0,1]
	v_cvt_pk_bf16_f32 v93, v94, v95
	v_pk_mul_f32 v[94:95], v[88:89], v[142:143] op_sel_hi:[1,0]
	s_nop 0
	v_pk_fma_f32 v[96:97], v[88:89], v[138:139], v[94:95] op_sel:[0,0,1] op_sel_hi:[1,1,0] neg_lo:[0,0,1] neg_hi:[0,0,1]
	v_pk_fma_f32 v[88:89], v[88:89], v[138:139], v[94:95] op_sel:[0,0,1] op_sel_hi:[1,0,0]
	s_nop 0
	v_mov_b32_e32 v97, v89
	v_pk_mul_f32 v[88:89], v[152:153], v[96:97] op_sel_hi:[0,1]
	v_mov_b32_e32 v96, v143
	v_cvt_pk_bf16_f32 v94, v88, v89
	v_mov_b32_e32 v88, v139
	v_pk_mul_f32 v[98:99], v[90:91], v[96:97] op_sel_hi:[1,0]
	s_nop 0
	v_pk_fma_f32 v[102:103], v[90:91], v[88:89], v[98:99] op_sel:[0,0,1] op_sel_hi:[1,0,0] neg_lo:[0,0,1] neg_hi:[0,0,1]
	v_pk_fma_f32 v[90:91], v[90:91], v[88:89], v[98:99] op_sel:[0,0,1] op_sel_hi:[1,0,0]
	v_lshl_add_u64 v[98:99], v[170:171], 0, s[22:23]
	v_mov_b32_e32 v103, v91
; __device__ __forceinline__ unsigned pk_bf16(float lo, float hi) { typedef __bf16 b2 __attribute__((ext_vector_type(2))); f32x2 v = {lo, hi}; b2 b = __builtin_convertvector(v, b2); return __builtin_bit_cast(unsigned, b); }
;     __device__ __forceinline__ void operator()(const f32x4 (&acc)[2][2][4][2], const Unit& u, int wr, int wc, int fr, int fq) const {
;     ...
;                 for (int ai = 0; ai < 2; ++ai) { f32x4 cc[4], ss[4];
; #pragma unroll
;                     for (int m = 0; m < 4; ++m) { const int row = row0 + ai * 128 + m * 16; cc[m] = *(const f32x4*)(cosT + (size_t)row * 32 + jb); ss[m] = *(const f32x4*)(sinT + (size_t)row * 32 + jb); }
; #pragma unroll
;                     for (int m = 0; m < 4; ++m) { const int row = row0 + ai * 128 + m * 16; const f32x4 c = cc[m], s = ss[m];
;                         u16* rowp = ZB + ((size_t)(pn * 4 + (wc >> 1)) * TT + row) * 64 + (lc & 63);
; #pragma unroll
;                         for (int bj = 0; bj < 2; ++bj) { const f32x4 v0 = acc[ai][bj][m][0], v1 = acc[ai][bj][m][1]; u32x4 w;
;                             w.x = pk_bf16((v0[0] * c[0] - v0[1] * s[0]) * sc, (v0[1] * c[0] + v0[0] * s[0]) * sc);
;                             w.y = pk_bf16((v0[2] * c[1] - v0[3] * s[1]) * sc, (v0[3] * c[1] + v0[2] * s[1]) * sc);
;                             w.z = pk_bf16((v1[0] * c[2] - v1[1] * s[2]) * sc, (v1[1] * c[2] + v1[0] * s[2]) * sc);
;                             w.w = pk_bf16((v1[2] * c[3] - v1[3] * s[3]) * sc, (v1[3] * c[3] + v1[2] * s[3]) * sc);
;                             *(u32x4*)(rowp + (size_t)bj * 2 * TT * 64) = w; } } }
	v_pk_mul_f32 v[90:91], v[152:153], v[102:103] op_sel_hi:[0,1]
	v_cvt_pk_bf16_f32 v95, v90, v91
	v_pk_mul_f32 v[90:91], v[84:85], v[140:141] op_sel_hi:[1,0]
	global_store_dwordx4 v[100:101], v[92:95], off
	v_lshl_add_u64 v[102:103], v[170:171], 0, s[26:27]
	s_nop 0
	v_pk_fma_f32 v[92:93], v[84:85], v[136:137], v[90:91] op_sel:[0,0,1] op_sel_hi:[1,1,0] neg_lo:[0,0,1] neg_hi:[0,0,1]
	v_pk_fma_f32 v[84:85], v[84:85], v[136:137], v[90:91] op_sel:[0,0,1] op_sel_hi:[1,0,0]
	v_pk_mul_f32 v[90:91], v[86:87], v[140:141] op_sel:[0,1]
	v_mov_b32_e32 v93, v85
	v_pk_mul_f32 v[84:85], v[152:153], v[92:93] op_sel_hi:[0,1]
	v_pk_fma_f32 v[92:93], v[86:87], v[136:137], v[90:91] op_sel:[0,1,1] op_sel_hi:[1,1,0] neg_lo:[0,0,1] neg_hi:[0,0,1]
	v_pk_fma_f32 v[86:87], v[86:87], v[136:137], v[90:91] op_sel:[0,1,1] op_sel_hi:[1,1,0]
	v_cvt_pk_bf16_f32 v84, v84, v85
	v_mov_b32_e32 v93, v87
	v_pk_mul_f32 v[86:87], v[152:153], v[92:93] op_sel_hi:[0,1]
	v_cvt_pk_bf16_f32 v85, v86, v87
	v_pk_mul_f32 v[86:87], v[76:77], v[142:143] op_sel_hi:[1,0]
	s_nop 0
	v_pk_fma_f32 v[90:91], v[76:77], v[138:139], v[86:87] op_sel:[0,0,1] op_sel_hi:[1,1,0] neg_lo:[0,0,1] neg_hi:[0,0,1]
	v_pk_fma_f32 v[76:77], v[76:77], v[138:139], v[86:87] op_sel:[0,0,1] op_sel_hi:[1,0,0]
	s_nop 0
	v_mov_b32_e32 v91, v77
	v_pk_mul_f32 v[76:77], v[152:153], v[90:91] op_sel_hi:[0,1]
	v_cvt_pk_bf16_f32 v86, v76, v77
	v_pk_mul_f32 v[76:77], v[78:79], v[96:97] op_sel_hi:[1,0]
	s_nop 0
	v_pk_fma_f32 v[90:91], v[78:79], v[88:89], v[76:77] op_sel:[0,0,1] op_sel_hi:[1,0,0] neg_lo:[0,0,1] neg_hi:[0,0,1]
	v_pk_fma_f32 v[76:77], v[78:79], v[88:89], v[76:77] op_sel:[0,0,1] op_sel_hi:[1,0,0]
	s_nop 0
	v_mov_b32_e32 v91, v77
	v_pk_mul_f32 v[76:77], v[152:153], v[90:91] op_sel_hi:[0,1]
	v_cvt_pk_bf16_f32 v87, v76, v77
	v_add_co_u32_e32 v76, vcc, s89, v100
	s_nop 1
	v_addc_co_u32_e32 v77, vcc, 0, v101, vcc
	global_store_dwordx4 v[76:77], v[84:87], off
	v_lshl_add_u64 v[246:247], v[170:171], 0, s[28:29]
	v_lshl_add_u64 v[250:251], v[156:157], 0, v[246:247]
	global_load_dwordx4 v[136:139], v[250:251], off
	v_lshl_add_u64 v[246:247], v[170:171], 0, s[28:29]
	v_lshl_add_u64 v[250:251], v[158:159], 0, v[246:247]
	global_load_dwordx4 v[140:143], v[250:251], off
	v_pk_mul_f32 v[76:77], v[80:81], v[132:133] op_sel_hi:[1,0]
	v_lshl_add_u64 v[100:101], v[170:171], 0, s[24:25]
	v_pk_fma_f32 v[78:79], v[80:81], v[128:129], v[76:77] op_sel:[0,0,1] op_sel_hi:[1,1,0] neg_lo:[0,0,1] neg_hi:[0,0,1]
	v_pk_fma_f32 v[76:77], v[80:81], v[128:129], v[76:77] op_sel:[0,0,1] op_sel_hi:[1,0,0]
	v_lshl_add_u64 v[84:85], v[168:169], 0, v[172:173]
	v_mov_b32_e32 v79, v77
	v_pk_mul_f32 v[76:77], v[152:153], v[78:79] op_sel_hi:[0,1]
	v_pk_mul_f32 v[78:79], v[82:83], v[132:133] op_sel:[0,1]
	v_cvt_pk_bf16_f32 v76, v76, v77
	v_pk_fma_f32 v[80:81], v[82:83], v[128:129], v[78:79] op_sel:[0,1,1] op_sel_hi:[1,1,0] neg_lo:[0,0,1] neg_hi:[0,0,1]
	v_pk_fma_f32 v[78:79], v[82:83], v[128:129], v[78:79] op_sel:[0,1,1] op_sel_hi:[1,1,0]
	s_nop 0
	v_mov_b32_e32 v81, v79
	v_pk_mul_f32 v[78:79], v[152:153], v[80:81] op_sel_hi:[0,1]
	v_cvt_pk_bf16_f32 v77, v78, v79
	v_pk_mul_f32 v[78:79], v[72:73], v[134:135] op_sel_hi:[1,0]
	s_nop 0
	v_pk_fma_f32 v[80:81], v[72:73], v[130:131], v[78:79] op_sel:[0,0,1] op_sel_hi:[1,1,0] neg_lo:[0,0,1] neg_hi:[0,0,1]
	v_pk_fma_f32 v[72:73], v[72:73], v[130:131], v[78:79] op_sel:[0,0,1] op_sel_hi:[1,0,0]
	s_nop 0
	v_mov_b32_e32 v81, v73
	v_pk_mul_f32 v[72:73], v[152:153], v[80:81] op_sel_hi:[0,1]
	v_mov_b32_e32 v80, v135
	v_cvt_pk_bf16_f32 v78, v72, v73
	v_mov_b32_e32 v72, v131
	v_pk_mul_f32 v[82:83], v[74:75], v[80:81] op_sel_hi:[1,0]
	s_nop 0
	v_pk_fma_f32 v[86:87], v[74:75], v[72:73], v[82:83] op_sel:[0,0,1] op_sel_hi:[1,0,0] neg_lo:[0,0,1] neg_hi:[0,0,1]
	v_pk_fma_f32 v[74:75], v[74:75], v[72:73], v[82:83] op_sel:[0,0,1] op_sel_hi:[1,0,0]
	s_nop 0
	v_mov_b32_e32 v87, v75
	v_pk_mul_f32 v[74:75], v[152:153], v[86:87] op_sel_hi:[0,1]
	v_cvt_pk_bf16_f32 v79, v74, v75
	v_pk_mul_f32 v[74:75], v[68:69], v[132:133] op_sel_hi:[1,0]
	global_store_dwordx4 v[84:85], v[76:79], off
	s_nop 1
	v_pk_fma_f32 v[76:77], v[68:69], v[128:129], v[74:75] op_sel:[0,0,1] op_sel_hi:[1,1,0] neg_lo:[0,0,1] neg_hi:[0,0,1]
	v_pk_fma_f32 v[68:69], v[68:69], v[128:129], v[74:75] op_sel:[0,0,1] op_sel_hi:[1,0,0]
	v_pk_mul_f32 v[74:75], v[70:71], v[132:133] op_sel:[0,1]
	v_mov_b32_e32 v77, v69
	v_pk_mul_f32 v[68:69], v[152:153], v[76:77] op_sel_hi:[0,1]
	v_pk_fma_f32 v[76:77], v[70:71], v[128:129], v[74:75] op_sel:[0,1,1] op_sel_hi:[1,1,0] neg_lo:[0,0,1] neg_hi:[0,0,1]
	v_pk_fma_f32 v[70:71], v[70:71], v[128:129], v[74:75] op_sel:[0,1,1] op_sel_hi:[1,1,0]
	v_cvt_pk_bf16_f32 v68, v68, v69
	v_mov_b32_e32 v77, v71
	v_pk_mul_f32 v[70:71], v[152:153], v[76:77] op_sel_hi:[0,1]
	v_cvt_pk_bf16_f32 v69, v70, v71
	v_pk_mul_f32 v[70:71], v[64:65], v[134:135] op_sel_hi:[1,0]
	s_nop 0
	v_pk_fma_f32 v[74:75], v[64:65], v[130:131], v[70:71] op_sel:[0,0,1] op_sel_hi:[1,1,0] neg_lo:[0,0,1] neg_hi:[0,0,1]
	v_pk_fma_f32 v[64:65], v[64:65], v[130:131], v[70:71] op_sel:[0,0,1] op_sel_hi:[1,0,0]
	s_nop 0
	v_mov_b32_e32 v75, v65
	v_pk_mul_f32 v[64:65], v[152:153], v[74:75] op_sel_hi:[0,1]
	v_cvt_pk_bf16_f32 v70, v64, v65
	v_pk_mul_f32 v[64:65], v[66:67], v[80:81] op_sel_hi:[1,0]
	s_nop 0
	v_pk_fma_f32 v[74:75], v[66:67], v[72:73], v[64:65] op_sel:[0,0,1] op_sel_hi:[1,0,0] neg_lo:[0,0,1] neg_hi:[0,0,1]
	v_pk_fma_f32 v[64:65], v[66:67], v[72:73], v[64:65] op_sel:[0,0,1] op_sel_hi:[1,0,0]
	v_lshl_add_u64 v[66:67], v[158:159], 0, v[98:99]
	v_mov_b32_e32 v75, v65
	v_pk_mul_f32 v[64:65], v[152:153], v[74:75] op_sel_hi:[0,1]
	v_cvt_pk_bf16_f32 v71, v64, v65
	v_add_co_u32_e32 v64, vcc, s89, v84
	v_lshl_add_u64 v[72:73], v[170:171], 0, s[28:29]
	s_nop 0
	v_addc_co_u32_e32 v65, vcc, 0, v85, vcc
	global_store_dwordx4 v[64:65], v[68:71], off
	v_lshl_add_u64 v[64:65], v[156:157], 0, v[98:99]
	v_lshl_add_u64 v[66:67], v[158:159], 0, v[100:101]
	v_lshl_add_u64 v[64:65], v[156:157], 0, v[100:101]
	v_lshl_add_u64 v[64:65], v[156:157], 0, v[102:103]
	v_lshl_add_u64 v[66:67], v[158:159], 0, v[102:103]
	v_lshl_add_u64 v[64:65], v[156:157], 0, v[72:73]
	v_lshl_add_u64 v[68:69], v[158:159], 0, v[72:73]
	s_nop 0
	v_lshl_add_u64 v[98:99], v[168:169], 0, v[98:99]
	s_waitcnt vmcnt(13)
; __device__ __forceinline__ unsigned pk_bf16(float lo, float hi) { typedef __bf16 b2 __attribute__((ext_vector_type(2))); f32x2 v = {lo, hi}; b2 b = __builtin_convertvector(v, b2); return __builtin_bit_cast(unsigned, b); }
;     __device__ __forceinline__ void operator()(const f32x4 (&acc)[2][2][4][2], const Unit& u, int wr, int wc, int fr, int fq) const {
;     ...
;                 for (int ai = 0; ai < 2; ++ai) { f32x4 cc[4], ss[4];
; #pragma unroll
;                     for (int m = 0; m < 4; ++m) { const int row = row0 + ai * 128 + m * 16; cc[m] = *(const f32x4*)(cosT + (size_t)row * 32 + jb); ss[m] = *(const f32x4*)(sinT + (size_t)row * 32 + jb); }
; #pragma unroll
;                     for (int m = 0; m < 4; ++m) { const int row = row0 + ai * 128 + m * 16; const f32x4 c = cc[m], s = ss[m];
;                         u16* rowp = ZB + ((size_t)(pn * 4 + (wc >> 1)) * TT + row) * 64 + (lc & 63);
; #pragma unroll
;                         for (int bj = 0; bj < 2; ++bj) { const f32x4 v0 = acc[ai][bj][m][0], v1 = acc[ai][bj][m][1]; u32x4 w;
;                             w.x = pk_bf16((v0[0] * c[0] - v0[1] * s[0]) * sc, (v0[1] * c[0] + v0[0] * s[0]) * sc);
;                             w.y = pk_bf16((v0[2] * c[1] - v0[3] * s[1]) * sc, (v0[3] * c[1] + v0[2] * s[1]) * sc);
;                             w.z = pk_bf16((v1[0] * c[2] - v1[1] * s[2]) * sc, (v1[1] * c[2] + v1[0] * s[2]) * sc);
;                             w.w = pk_bf16((v1[2] * c[3] - v1[3] * s[3]) * sc, (v1[3] * c[3] + v1[2] * s[3]) * sc);
;                             *(u32x4*)(rowp + (size_t)bj * 2 * TT * 64) = w; } } }
	v_pk_mul_f32 v[104:105], v[60:61], v[236:237] op_sel_hi:[1,0]
	s_waitcnt vmcnt(12)
	v_pk_fma_f32 v[106:107], v[60:61], v[242:243], v[104:105] op_sel:[0,0,1] op_sel_hi:[1,1,0] neg_lo:[0,0,1] neg_hi:[0,0,1]
	v_pk_fma_f32 v[60:61], v[60:61], v[242:243], v[104:105] op_sel:[0,0,1] op_sel_hi:[1,0,0]
	v_pk_mul_f32 v[104:105], v[62:63], v[236:237] op_sel:[0,1]
	v_mov_b32_e32 v107, v61
	v_pk_mul_f32 v[60:61], v[152:153], v[106:107] op_sel_hi:[0,1]
	v_pk_fma_f32 v[106:107], v[62:63], v[242:243], v[104:105] op_sel:[0,1,1] op_sel_hi:[1,1,0] neg_lo:[0,0,1] neg_hi:[0,0,1]
	v_pk_fma_f32 v[62:63], v[62:63], v[242:243], v[104:105] op_sel:[0,1,1] op_sel_hi:[1,1,0]
	v_cvt_pk_bf16_f32 v60, v60, v61
	v_mov_b32_e32 v107, v63
	v_pk_mul_f32 v[62:63], v[152:153], v[106:107] op_sel_hi:[0,1]
	v_cvt_pk_bf16_f32 v61, v62, v63
	v_pk_mul_f32 v[62:63], v[56:57], v[238:239] op_sel_hi:[1,0]
	s_nop 0
	v_pk_fma_f32 v[104:105], v[56:57], v[244:245], v[62:63] op_sel:[0,0,1] op_sel_hi:[1,1,0] neg_lo:[0,0,1] neg_hi:[0,0,1]
	v_pk_fma_f32 v[56:57], v[56:57], v[244:245], v[62:63] op_sel:[0,0,1] op_sel_hi:[1,0,0]
	s_nop 0
	v_mov_b32_e32 v105, v57
	v_pk_mul_f32 v[56:57], v[152:153], v[104:105] op_sel_hi:[0,1]
	v_mov_b32_e32 v104, v239
	v_cvt_pk_bf16_f32 v62, v56, v57
	v_mov_b32_e32 v56, v245
	v_pk_mul_f32 v[106:107], v[58:59], v[104:105] op_sel_hi:[1,0]
	s_nop 0
	v_pk_fma_f32 v[108:109], v[58:59], v[56:57], v[106:107] op_sel:[0,0,1] op_sel_hi:[1,0,0] neg_lo:[0,0,1] neg_hi:[0,0,1]
	v_pk_fma_f32 v[58:59], v[58:59], v[56:57], v[106:107] op_sel:[0,0,1] op_sel_hi:[1,0,0]
	s_nop 0
	v_mov_b32_e32 v109, v59
	v_pk_mul_f32 v[58:59], v[152:153], v[108:109] op_sel_hi:[0,1]
	v_cvt_pk_bf16_f32 v63, v58, v59
	v_pk_mul_f32 v[58:59], v[52:53], v[236:237] op_sel_hi:[1,0]
	global_store_dwordx4 v[98:99], v[60:63], off
	s_nop 1
	v_pk_fma_f32 v[60:61], v[52:53], v[242:243], v[58:59] op_sel:[0,0,1] op_sel_hi:[1,1,0] neg_lo:[0,0,1] neg_hi:[0,0,1]
	v_pk_fma_f32 v[52:53], v[52:53], v[242:243], v[58:59] op_sel:[0,0,1] op_sel_hi:[1,0,0]
	v_pk_mul_f32 v[58:59], v[54:55], v[236:237] op_sel:[0,1]
	v_mov_b32_e32 v61, v53
	v_pk_mul_f32 v[52:53], v[152:153], v[60:61] op_sel_hi:[0,1]
	v_pk_fma_f32 v[60:61], v[54:55], v[242:243], v[58:59] op_sel:[0,1,1] op_sel_hi:[1,1,0] neg_lo:[0,0,1] neg_hi:[0,0,1]
	v_pk_fma_f32 v[54:55], v[54:55], v[242:243], v[58:59] op_sel:[0,1,1] op_sel_hi:[1,1,0]
	v_cvt_pk_bf16_f32 v52, v52, v53
	v_mov_b32_e32 v61, v55
	v_pk_mul_f32 v[54:55], v[152:153], v[60:61] op_sel_hi:[0,1]
	v_cvt_pk_bf16_f32 v53, v54, v55
	v_pk_mul_f32 v[54:55], v[44:45], v[238:239] op_sel_hi:[1,0]
	s_nop 0
	v_pk_fma_f32 v[58:59], v[44:45], v[244:245], v[54:55] op_sel:[0,0,1] op_sel_hi:[1,1,0] neg_lo:[0,0,1] neg_hi:[0,0,1]
	v_pk_fma_f32 v[44:45], v[44:45], v[244:245], v[54:55] op_sel:[0,0,1] op_sel_hi:[1,0,0]
	s_nop 0
	v_mov_b32_e32 v59, v45
	v_pk_mul_f32 v[44:45], v[152:153], v[58:59] op_sel_hi:[0,1]
	v_cvt_pk_bf16_f32 v54, v44, v45
	v_pk_mul_f32 v[44:45], v[46:47], v[104:105] op_sel_hi:[1,0]
	s_nop 0
	v_pk_fma_f32 v[58:59], v[46:47], v[56:57], v[44:45] op_sel:[0,0,1] op_sel_hi:[1,0,0] neg_lo:[0,0,1] neg_hi:[0,0,1]
	v_pk_fma_f32 v[44:45], v[46:47], v[56:57], v[44:45] op_sel:[0,0,1] op_sel_hi:[1,0,0]
	s_nop 0
	v_mov_b32_e32 v59, v45
	v_pk_mul_f32 v[44:45], v[152:153], v[58:59] op_sel_hi:[0,1]
	v_cvt_pk_bf16_f32 v55, v44, v45
	v_add_co_u32_e32 v44, vcc, s89, v98
	s_nop 1
	v_addc_co_u32_e32 v45, vcc, 0, v99, vcc
	global_store_dwordx4 v[44:45], v[52:55], off
	s_waitcnt vmcnt(13)
	v_pk_mul_f32 v[44:45], v[48:49], v[182:183] op_sel_hi:[1,0]
	s_waitcnt vmcnt(12)
	v_pk_fma_f32 v[46:47], v[48:49], v[190:191], v[44:45] op_sel:[0,0,1] op_sel_hi:[1,1,0] neg_lo:[0,0,1] neg_hi:[0,0,1]
	v_pk_fma_f32 v[44:45], v[48:49], v[190:191], v[44:45] op_sel:[0,0,1] op_sel_hi:[1,0,0]
	v_lshl_add_u64 v[52:53], v[168:169], 0, v[100:101]
	v_mov_b32_e32 v47, v45
	v_pk_mul_f32 v[44:45], v[152:153], v[46:47] op_sel_hi:[0,1]
	v_pk_mul_f32 v[46:47], v[50:51], v[182:183] op_sel:[0,1]
	v_cvt_pk_bf16_f32 v44, v44, v45
	v_pk_fma_f32 v[48:49], v[50:51], v[190:191], v[46:47] op_sel:[0,1,1] op_sel_hi:[1,1,0] neg_lo:[0,0,1] neg_hi:[0,0,1]
	v_pk_fma_f32 v[46:47], v[50:51], v[190:191], v[46:47] op_sel:[0,1,1] op_sel_hi:[1,1,0]
	s_nop 0
	v_mov_b32_e32 v49, v47
	v_pk_mul_f32 v[46:47], v[152:153], v[48:49] op_sel_hi:[0,1]
	v_cvt_pk_bf16_f32 v45, v46, v47
	v_pk_mul_f32 v[46:47], v[40:41], v[184:185] op_sel_hi:[1,0]
	s_nop 0
	v_pk_fma_f32 v[48:49], v[40:41], v[192:193], v[46:47] op_sel:[0,0,1] op_sel_hi:[1,1,0] neg_lo:[0,0,1] neg_hi:[0,0,1]
	v_pk_fma_f32 v[40:41], v[40:41], v[192:193], v[46:47] op_sel:[0,0,1] op_sel_hi:[1,0,0]
	s_nop 0
	v_mov_b32_e32 v49, v41
	v_pk_mul_f32 v[40:41], v[152:153], v[48:49] op_sel_hi:[0,1]
	v_mov_b32_e32 v48, v185
	v_cvt_pk_bf16_f32 v46, v40, v41
	v_mov_b32_e32 v40, v193
	v_pk_mul_f32 v[50:51], v[42:43], v[48:49] op_sel_hi:[1,0]
	s_nop 0
	v_pk_fma_f32 v[54:55], v[42:43], v[40:41], v[50:51] op_sel:[0,0,1] op_sel_hi:[1,0,0] neg_lo:[0,0,1] neg_hi:[0,0,1]
	v_pk_fma_f32 v[42:43], v[42:43], v[40:41], v[50:51] op_sel:[0,0,1] op_sel_hi:[1,0,0]
	s_nop 0
	v_mov_b32_e32 v55, v43
	v_pk_mul_f32 v[42:43], v[152:153], v[54:55] op_sel_hi:[0,1]
	v_cvt_pk_bf16_f32 v47, v42, v43
	v_pk_mul_f32 v[42:43], v[36:37], v[182:183] op_sel_hi:[1,0]
	global_store_dwordx4 v[52:53], v[44:47], off
	s_nop 1
	v_pk_fma_f32 v[44:45], v[36:37], v[190:191], v[42:43] op_sel:[0,0,1] op_sel_hi:[1,1,0] neg_lo:[0,0,1] neg_hi:[0,0,1]
	v_pk_fma_f32 v[36:37], v[36:37], v[190:191], v[42:43] op_sel:[0,0,1] op_sel_hi:[1,0,0]
	v_pk_mul_f32 v[42:43], v[38:39], v[182:183] op_sel:[0,1]
	v_mov_b32_e32 v45, v37
	v_pk_mul_f32 v[36:37], v[152:153], v[44:45] op_sel_hi:[0,1]
	v_pk_fma_f32 v[44:45], v[38:39], v[190:191], v[42:43] op_sel:[0,1,1] op_sel_hi:[1,1,0] neg_lo:[0,0,1] neg_hi:[0,0,1]
	v_pk_fma_f32 v[38:39], v[38:39], v[190:191], v[42:43] op_sel:[0,1,1] op_sel_hi:[1,1,0]
	v_cvt_pk_bf16_f32 v36, v36, v37
	v_mov_b32_e32 v45, v39
	v_pk_mul_f32 v[38:39], v[152:153], v[44:45] op_sel_hi:[0,1]
	v_cvt_pk_bf16_f32 v37, v38, v39
	v_pk_mul_f32 v[38:39], v[28:29], v[184:185] op_sel_hi:[1,0]
	s_nop 0
	v_pk_fma_f32 v[42:43], v[28:29], v[192:193], v[38:39] op_sel:[0,0,1] op_sel_hi:[1,1,0] neg_lo:[0,0,1] neg_hi:[0,0,1]
	v_pk_fma_f32 v[28:29], v[28:29], v[192:193], v[38:39] op_sel:[0,0,1] op_sel_hi:[1,0,0]
	s_nop 0
	v_mov_b32_e32 v43, v29
	v_pk_mul_f32 v[28:29], v[152:153], v[42:43] op_sel_hi:[0,1]
	v_cvt_pk_bf16_f32 v38, v28, v29
	v_pk_mul_f32 v[28:29], v[30:31], v[48:49] op_sel_hi:[1,0]
	s_nop 0
	v_pk_fma_f32 v[42:43], v[30:31], v[40:41], v[28:29] op_sel:[0,0,1] op_sel_hi:[1,0,0] neg_lo:[0,0,1] neg_hi:[0,0,1]
	v_pk_fma_f32 v[28:29], v[30:31], v[40:41], v[28:29] op_sel:[0,0,1] op_sel_hi:[1,0,0]
	s_nop 0
	v_mov_b32_e32 v43, v29
	v_pk_mul_f32 v[28:29], v[152:153], v[42:43] op_sel_hi:[0,1]
	v_cvt_pk_bf16_f32 v39, v28, v29
	v_add_co_u32_e32 v28, vcc, s89, v52
	s_nop 1
	v_addc_co_u32_e32 v29, vcc, 0, v53, vcc
	global_store_dwordx4 v[28:29], v[36:39], off
	s_waitcnt vmcnt(10)
; __device__ __forceinline__ unsigned pk_bf16(float lo, float hi) { typedef __bf16 b2 __attribute__((ext_vector_type(2))); f32x2 v = {lo, hi}; b2 b = __builtin_convertvector(v, b2); return __builtin_bit_cast(unsigned, b); }
;     __device__ __forceinline__ void operator()(const f32x4 (&acc)[2][2][4][2], const Unit& u, int wr, int wc, int fr, int fq) const {
;     ...
;                 for (int ai = 0; ai < 2; ++ai) { f32x4 cc[4], ss[4];
; #pragma unroll
;                     for (int m = 0; m < 4; ++m) { const int row = row0 + ai * 128 + m * 16; cc[m] = *(const f32x4*)(cosT + (size_t)row * 32 + jb); ss[m] = *(const f32x4*)(sinT + (size_t)row * 32 + jb); }
; #pragma unroll
;                     for (int m = 0; m < 4; ++m) { const int row = row0 + ai * 128 + m * 16; const f32x4 c = cc[m], s = ss[m];
;                         u16* rowp = ZB + ((size_t)(pn * 4 + (wc >> 1)) * TT + row) * 64 + (lc & 63);
; #pragma unroll
;                         for (int bj = 0; bj < 2; ++bj) { const f32x4 v0 = acc[ai][bj][m][0], v1 = acc[ai][bj][m][1]; u32x4 w;
;                             w.x = pk_bf16((v0[0] * c[0] - v0[1] * s[0]) * sc, (v0[1] * c[0] + v0[0] * s[0]) * sc);
;                             w.y = pk_bf16((v0[2] * c[1] - v0[3] * s[1]) * sc, (v0[3] * c[1] + v0[2] * s[1]) * sc);
;                             w.z = pk_bf16((v1[0] * c[2] - v1[1] * s[2]) * sc, (v1[1] * c[2] + v1[0] * s[2]) * sc);
;                             w.w = pk_bf16((v1[2] * c[3] - v1[3] * s[3]) * sc, (v1[3] * c[3] + v1[2] * s[3]) * sc);
;                             *(u32x4*)(rowp + (size_t)bj * 2 * TT * 64) = w; } } }
	v_pk_mul_f32 v[28:29], v[32:33], v[198:199] op_sel_hi:[1,0]
	s_nop 0
	v_pk_fma_f32 v[30:31], v[32:33], v[194:195], v[28:29] op_sel:[0,0,1] op_sel_hi:[1,1,0] neg_lo:[0,0,1] neg_hi:[0,0,1]
	v_pk_fma_f32 v[28:29], v[32:33], v[194:195], v[28:29] op_sel:[0,0,1] op_sel_hi:[1,0,0]
	v_lshl_add_u64 v[36:37], v[168:169], 0, v[102:103]
	v_mov_b32_e32 v31, v29
	v_pk_mul_f32 v[28:29], v[152:153], v[30:31] op_sel_hi:[0,1]
	v_pk_mul_f32 v[30:31], v[34:35], v[198:199] op_sel:[0,1]
	v_cvt_pk_bf16_f32 v28, v28, v29
	v_pk_fma_f32 v[32:33], v[34:35], v[194:195], v[30:31] op_sel:[0,1,1] op_sel_hi:[1,1,0] neg_lo:[0,0,1] neg_hi:[0,0,1]
	v_pk_fma_f32 v[30:31], v[34:35], v[194:195], v[30:31] op_sel:[0,1,1] op_sel_hi:[1,1,0]
	s_nop 0
	v_mov_b32_e32 v33, v31
	v_pk_mul_f32 v[30:31], v[152:153], v[32:33] op_sel_hi:[0,1]
	v_cvt_pk_bf16_f32 v29, v30, v31
	v_pk_mul_f32 v[30:31], v[24:25], v[200:201] op_sel_hi:[1,0]
	s_nop 0
	v_pk_fma_f32 v[32:33], v[24:25], v[196:197], v[30:31] op_sel:[0,0,1] op_sel_hi:[1,1,0] neg_lo:[0,0,1] neg_hi:[0,0,1]
	v_pk_fma_f32 v[24:25], v[24:25], v[196:197], v[30:31] op_sel:[0,0,1] op_sel_hi:[1,0,0]
	s_nop 0
	v_mov_b32_e32 v33, v25
	v_pk_mul_f32 v[24:25], v[152:153], v[32:33] op_sel_hi:[0,1]
	v_mov_b32_e32 v32, v201
	v_cvt_pk_bf16_f32 v30, v24, v25
	v_mov_b32_e32 v24, v197
	v_pk_mul_f32 v[34:35], v[26:27], v[32:33] op_sel_hi:[1,0]
	s_nop 0
	v_pk_fma_f32 v[38:39], v[26:27], v[24:25], v[34:35] op_sel:[0,0,1] op_sel_hi:[1,0,0] neg_lo:[0,0,1] neg_hi:[0,0,1]
	v_pk_fma_f32 v[26:27], v[26:27], v[24:25], v[34:35] op_sel:[0,0,1] op_sel_hi:[1,0,0]
	s_nop 0
	v_mov_b32_e32 v39, v27
	v_pk_mul_f32 v[26:27], v[152:153], v[38:39] op_sel_hi:[0,1]
	v_cvt_pk_bf16_f32 v31, v26, v27
	v_pk_mul_f32 v[26:27], v[20:21], v[198:199] op_sel_hi:[1,0]
	global_store_dwordx4 v[36:37], v[28:31], off
	s_nop 1
	v_pk_fma_f32 v[28:29], v[20:21], v[194:195], v[26:27] op_sel:[0,0,1] op_sel_hi:[1,1,0] neg_lo:[0,0,1] neg_hi:[0,0,1]
	v_pk_fma_f32 v[20:21], v[20:21], v[194:195], v[26:27] op_sel:[0,0,1] op_sel_hi:[1,0,0]
	v_pk_mul_f32 v[26:27], v[22:23], v[198:199] op_sel:[0,1]
	v_mov_b32_e32 v29, v21
	v_pk_mul_f32 v[20:21], v[152:153], v[28:29] op_sel_hi:[0,1]
	v_pk_fma_f32 v[28:29], v[22:23], v[194:195], v[26:27] op_sel:[0,1,1] op_sel_hi:[1,1,0] neg_lo:[0,0,1] neg_hi:[0,0,1]
	v_pk_fma_f32 v[22:23], v[22:23], v[194:195], v[26:27] op_sel:[0,1,1] op_sel_hi:[1,1,0]
	v_cvt_pk_bf16_f32 v20, v20, v21
	v_mov_b32_e32 v29, v23
	v_pk_mul_f32 v[22:23], v[152:153], v[28:29] op_sel_hi:[0,1]
	v_cvt_pk_bf16_f32 v21, v22, v23
	v_pk_mul_f32 v[22:23], v[12:13], v[200:201] op_sel_hi:[1,0]
	s_nop 0
	v_pk_fma_f32 v[26:27], v[12:13], v[196:197], v[22:23] op_sel:[0,0,1] op_sel_hi:[1,1,0] neg_lo:[0,0,1] neg_hi:[0,0,1]
	v_pk_fma_f32 v[12:13], v[12:13], v[196:197], v[22:23] op_sel:[0,0,1] op_sel_hi:[1,0,0]
	s_nop 0
	v_mov_b32_e32 v27, v13
	v_pk_mul_f32 v[12:13], v[152:153], v[26:27] op_sel_hi:[0,1]
	v_cvt_pk_bf16_f32 v22, v12, v13
	v_pk_mul_f32 v[12:13], v[14:15], v[32:33] op_sel_hi:[1,0]
	s_nop 0
	v_pk_fma_f32 v[26:27], v[14:15], v[24:25], v[12:13] op_sel:[0,0,1] op_sel_hi:[1,0,0] neg_lo:[0,0,1] neg_hi:[0,0,1]
	v_pk_fma_f32 v[12:13], v[14:15], v[24:25], v[12:13] op_sel:[0,0,1] op_sel_hi:[1,0,0]
	s_nop 0
	v_mov_b32_e32 v27, v13
	v_pk_mul_f32 v[12:13], v[152:153], v[26:27] op_sel_hi:[0,1]
	v_cvt_pk_bf16_f32 v23, v12, v13
	v_add_co_u32_e32 v12, vcc, s89, v36
	s_nop 1
	v_addc_co_u32_e32 v13, vcc, 0, v37, vcc
	global_store_dwordx4 v[12:13], v[20:23], off
	s_waitcnt vmcnt(8)
	v_pk_mul_f32 v[12:13], v[16:17], v[140:141] op_sel_hi:[1,0]
	s_nop 0
	v_pk_fma_f32 v[14:15], v[16:17], v[136:137], v[12:13] op_sel:[0,0,1] op_sel_hi:[1,1,0] neg_lo:[0,0,1] neg_hi:[0,0,1]
	v_pk_fma_f32 v[12:13], v[16:17], v[136:137], v[12:13] op_sel:[0,0,1] op_sel_hi:[1,0,0]
	v_lshl_add_u64 v[20:21], v[168:169], 0, v[72:73]
	v_mov_b32_e32 v15, v13
	v_pk_mul_f32 v[12:13], v[152:153], v[14:15] op_sel_hi:[0,1]
	v_pk_mul_f32 v[14:15], v[18:19], v[140:141] op_sel:[0,1]
	v_cvt_pk_bf16_f32 v12, v12, v13
	v_pk_fma_f32 v[16:17], v[18:19], v[136:137], v[14:15] op_sel:[0,1,1] op_sel_hi:[1,1,0] neg_lo:[0,0,1] neg_hi:[0,0,1]
	v_pk_fma_f32 v[14:15], v[18:19], v[136:137], v[14:15] op_sel:[0,1,1] op_sel_hi:[1,1,0]
	s_nop 0
	v_mov_b32_e32 v17, v15
	v_pk_mul_f32 v[14:15], v[152:153], v[16:17] op_sel_hi:[0,1]
	v_cvt_pk_bf16_f32 v13, v14, v15
	v_pk_mul_f32 v[14:15], v[8:9], v[142:143] op_sel_hi:[1,0]
	s_nop 0
	v_pk_fma_f32 v[16:17], v[8:9], v[138:139], v[14:15] op_sel:[0,0,1] op_sel_hi:[1,1,0] neg_lo:[0,0,1] neg_hi:[0,0,1]
	v_pk_fma_f32 v[8:9], v[8:9], v[138:139], v[14:15] op_sel:[0,0,1] op_sel_hi:[1,0,0]
	s_nop 0
	v_mov_b32_e32 v17, v9
	v_pk_mul_f32 v[8:9], v[152:153], v[16:17] op_sel_hi:[0,1]
	v_mov_b32_e32 v16, v143
	v_cvt_pk_bf16_f32 v14, v8, v9
	v_mov_b32_e32 v8, v139
	v_pk_mul_f32 v[18:19], v[10:11], v[16:17] op_sel_hi:[1,0]
	s_nop 0
	v_pk_fma_f32 v[22:23], v[10:11], v[8:9], v[18:19] op_sel:[0,0,1] op_sel_hi:[1,0,0] neg_lo:[0,0,1] neg_hi:[0,0,1]
	v_pk_fma_f32 v[10:11], v[10:11], v[8:9], v[18:19] op_sel:[0,0,1] op_sel_hi:[1,0,0]
	s_nop 0
	v_mov_b32_e32 v23, v11
	v_pk_mul_f32 v[10:11], v[152:153], v[22:23] op_sel_hi:[0,1]
	v_cvt_pk_bf16_f32 v15, v10, v11
	v_pk_mul_f32 v[10:11], v[4:5], v[140:141] op_sel_hi:[1,0]
	global_store_dwordx4 v[20:21], v[12:15], off
	s_nop 1
	v_pk_fma_f32 v[12:13], v[4:5], v[136:137], v[10:11] op_sel:[0,0,1] op_sel_hi:[1,1,0] neg_lo:[0,0,1] neg_hi:[0,0,1]
	v_pk_fma_f32 v[4:5], v[4:5], v[136:137], v[10:11] op_sel:[0,0,1] op_sel_hi:[1,0,0]
	v_pk_mul_f32 v[10:11], v[6:7], v[140:141] op_sel:[0,1]
	v_mov_b32_e32 v13, v5
	v_pk_mul_f32 v[4:5], v[152:153], v[12:13] op_sel_hi:[0,1]
	v_pk_fma_f32 v[12:13], v[6:7], v[136:137], v[10:11] op_sel:[0,1,1] op_sel_hi:[1,1,0] neg_lo:[0,0,1] neg_hi:[0,0,1]
	v_pk_fma_f32 v[6:7], v[6:7], v[136:137], v[10:11] op_sel:[0,1,1] op_sel_hi:[1,1,0]
	v_cvt_pk_bf16_f32 v4, v4, v5
	v_mov_b32_e32 v13, v7
	v_pk_mul_f32 v[6:7], v[152:153], v[12:13] op_sel_hi:[0,1]
	v_cvt_pk_bf16_f32 v5, v6, v7
	v_pk_mul_f32 v[6:7], v[0:1], v[142:143] op_sel_hi:[1,0]
	s_nop 0
	v_pk_fma_f32 v[10:11], v[0:1], v[138:139], v[6:7] op_sel:[0,0,1] op_sel_hi:[1,1,0] neg_lo:[0,0,1] neg_hi:[0,0,1]
	v_pk_fma_f32 v[0:1], v[0:1], v[138:139], v[6:7] op_sel:[0,0,1] op_sel_hi:[1,0,0]
	s_nop 0
	v_mov_b32_e32 v11, v1
	v_pk_mul_f32 v[0:1], v[152:153], v[10:11] op_sel_hi:[0,1]
	v_cvt_pk_bf16_f32 v6, v0, v1
	v_pk_mul_f32 v[0:1], v[2:3], v[16:17] op_sel_hi:[1,0]
	s_nop 0
	v_pk_fma_f32 v[10:11], v[2:3], v[8:9], v[0:1] op_sel:[0,0,1] op_sel_hi:[1,0,0] neg_lo:[0,0,1] neg_hi:[0,0,1]
	v_pk_fma_f32 v[0:1], v[2:3], v[8:9], v[0:1] op_sel:[0,0,1] op_sel_hi:[1,0,0]
	s_nop 0
	v_mov_b32_e32 v11, v1
	v_pk_mul_f32 v[0:1], v[152:153], v[10:11] op_sel_hi:[0,1]
	v_cvt_pk_bf16_f32 v7, v0, v1
	v_add_co_u32_e32 v0, vcc, 0x400000, v20
	s_nop 1
	v_addc_co_u32_e32 v1, vcc, 0, v21, vcc
	global_store_dwordx4 v[0:1], v[4:7], off
	s_andn2_b64 vcc, exec, s[0:1]
	s_mov_b64 s[0:1], -1
	s_cbranch_vccnz .LBB0_122
